# moba_select rewritten by hand: k block sums staged once per workgroup in LDS (broadcast ds_read_b128 instead of 56 global_load_dwordx4 per wave), packed f32 fma on natural pairs, pairwise rank count
# baseline (speedup 1.0000x reference)
; __device__ __forceinline__ unsigned moba_select(int b, int h, int qb, const f16_t* Q, const float* __restrict__ kms) {
;     int tid_ = threadIdx.x; asm volatile("" : "+v"(tid_));
;     const int tid = tid_, lane = tid & 63, r32 = lane & 31, hi = lane >> 5; const int wid = __builtin_amdgcn_readfirstlane(tid >> 6);
;     const f16_t* Qw = Q + ((long)b * SEQ + qb * QB + wid * QBLK) * QP + h * HD;
;     f16x8 qr[4];
; #pragma unroll
;     for (int d0 = 0; d0 < 4; ++d0) qr[d0] = *reinterpret_cast<const f16x8*>(&Qw[(long)r32 * QP + d0 * 16 + hi * 8]);
;     float gsc[7];
; #pragma unroll
;     for (int j = 0; j < 7; ++j) {
;         float s = 0.f;
;         if (j < qb) {
;             const float* km = kms + (size_t)(b * NBLK + j) * AW + h * HD + hi * 8;
; #pragma unroll
;             for (int d0 = 0; d0 < 4; ++d0) {
;                 const f32x4 k0 = *(const f32x4*)(km + d0 * 16), k1 = *(const f32x4*)(km + d0 * 16 + 4);
;                 s += (float)qr[d0][0] * k0[0] + (float)qr[d0][1] * k0[1] + (float)qr[d0][2] * k0[2] + (float)qr[d0][3] * k0[3];
;                 s += (float)qr[d0][4] * k1[0] + (float)qr[d0][5] * k1[1] + (float)qr[d0][6] * k1[2] + (float)qr[d0][7] * k1[3];
;             }
;             s += __shfl_xor(s, 32);
.LBB0_530:
	v_mov_b32_e32 v150, v0
	s_and_b64 s[0:1], s[2:3], exec
	s_cselect_b32 s70, s7, s78
	v_readfirstlane_b32 s24, v150
	v_and_b32_e32 v201, 63, v150
	s_ashr_i32 s29, s24, 6
	v_lshlrev_b32_e32 v190, 10, v201
	s_lshl_b32 s0, s29, 3
	v_lshl_add_u64 v[2:3], s[58:59], 0, v[190:191]
	s_ashr_i32 s1, s0, 31
	v_lshl_add_u64 v[182:183], s[0:1], 1, v[2:3]
	s_lshl_b32 s0, s29, 4
	v_bfe_u32 v2, v150, 2, 4
	v_and_or_b32 v2, s0, 48, v2
	s_ashr_i32 s0, s24, 3
	s_lshl_b32 s71, s70, 8
	s_andn2_b32 s0, s0, 31
	s_or_b32 s8, s56, s71
	v_lshlrev_b32_e32 v190, 10, v2
	s_ashr_i32 s1, s0, 31
	s_lshl_b32 s11, s29, 10
	v_lshl_add_u64 v[2:3], s[60:61], 0, v[190:191]
	v_lshlrev_b32_e32 v202, 3, v150
	s_cmp_lg_u32 0, -1
	v_lshl_add_u64 v[2:3], s[0:1], 1, v[2:3]
	v_and_b32_e32 v203, 24, v202
	s_cselect_b32 s0, 0, 0
	v_lshlrev_b32_e32 v190, 1, v203
	s_add_i32 s76, s11, s0
	s_mov_b32 s0, m0
	s_mov_b32 m0, s76
	s_nop 0
	global_load_lds_dwordx4 v[182:183], off
	s_mov_b32 m0, s0
	v_lshl_add_u64 v[104:105], v[2:3], 0, v[190:191]
	s_add_i32 s77, s76, 0x6000
	s_mov_b32 s0, m0
	s_mov_b32 m0, s77
	s_nop 0
	global_load_lds_dwordx4 v[104:105], off
	s_mov_b32 m0, s0
	v_lshl_add_u64 v[2:3], v[182:183], 0, s[42:43]
	s_add_i32 s0, s76, 0x2000
	s_mov_b32 s1, m0
	s_mov_b32 m0, s0
	s_nop 0
	global_load_lds_dwordx4 v[2:3], off
	s_mov_b32 m0, s1
	s_cmp_gt_u32 s70, 3
	s_cselect_b64 s[4:5], -1, 0
	s_cmp_lt_u32 s70, 4
	v_mov_b32_e32 v210, -1
	s_cbranch_scc1 .LBB0_538
	s_lshl_b32 s9, s29, 11
	s_add_u32 s36, s62, s64
	s_addc_u32 s37, s63, s65
	s_add_u32 s36, s36, s9
	s_addc_u32 s37, s37, 0
	v_lshlrev_b32_e32 v19, 2, v201
	global_load_dword v18, v19, s[36:37]
	s_lshl_b32 s0, s29, 5
	s_add_u32 s0, s8, s0
	s_addc_u32 s1, s57, 0
	s_lshl_b64 s[0:1], s[0:1], 11
	s_add_u32 s0, s79, s0
	s_addc_u32 s1, s14, s1
	v_and_b32_e32 v21, 31, v201
	v_lshrrev_b32_e32 v20, 5, v201
	v_lshlrev_b32_e32 v21, 11, v21
	v_lshl_or_b32 v21, v20, 4, v21
	global_load_dwordx4 v[2:5], v21, s[0:1]
	global_load_dwordx4 v[6:9], v21, s[0:1] offset:32
	global_load_dwordx4 v[10:13], v21, s[0:1] offset:64
	global_load_dwordx4 v[14:17], v21, s[0:1] offset:96
	s_mov_b32 s9, 0x15000
	s_lshl_b32 s30, s29, 8
	s_add_i32 s30, s30, s9
	v_add_u32_e32 v101, s30, v19
	v_lshl_add_u32 v100, v20, 5, s9
	s_waitcnt vmcnt(4)
	ds_write_b32 v101, v18
	s_waitcnt lgkmcnt(0)
	s_barrier
	ds_read_b128 v[54:57], v100 offset:0
	ds_read_b128 v[58:61], v100 offset:16
	ds_read_b128 v[62:65], v100 offset:64
	ds_read_b128 v[66:69], v100 offset:80
	ds_read_b128 v[70:73], v100 offset:128
	ds_read_b128 v[74:77], v100 offset:144
	ds_read_b128 v[78:81], v100 offset:192
	ds_read_b128 v[82:85], v100 offset:208
	ds_read_b128 v[106:109], v100 offset:256
	ds_read_b128 v[110:113], v100 offset:272
	ds_read_b128 v[114:117], v100 offset:320
	ds_read_b128 v[118:121], v100 offset:336
	ds_read_b128 v[122:125], v100 offset:384
	ds_read_b128 v[126:129], v100 offset:400
	ds_read_b128 v[130:133], v100 offset:448
	ds_read_b128 v[134:137], v100 offset:464
	s_waitcnt vmcnt(0)
	v_cvt_f32_f16_e32 v22, v2
	v_cvt_f32_f16_sdwa v23, v2 dst_sel:DWORD dst_unused:UNUSED_PAD src0_sel:WORD_1
	v_cvt_f32_f16_e32 v24, v3
	v_cvt_f32_f16_sdwa v25, v3 dst_sel:DWORD dst_unused:UNUSED_PAD src0_sel:WORD_1
	v_cvt_f32_f16_e32 v26, v4
	v_cvt_f32_f16_sdwa v27, v4 dst_sel:DWORD dst_unused:UNUSED_PAD src0_sel:WORD_1
	v_cvt_f32_f16_e32 v28, v5
	v_cvt_f32_f16_sdwa v29, v5 dst_sel:DWORD dst_unused:UNUSED_PAD src0_sel:WORD_1
	v_cvt_f32_f16_e32 v30, v6
	v_cvt_f32_f16_sdwa v31, v6 dst_sel:DWORD dst_unused:UNUSED_PAD src0_sel:WORD_1
	v_cvt_f32_f16_e32 v32, v7
	v_cvt_f32_f16_sdwa v33, v7 dst_sel:DWORD dst_unused:UNUSED_PAD src0_sel:WORD_1
	v_cvt_f32_f16_e32 v34, v8
	v_cvt_f32_f16_sdwa v35, v8 dst_sel:DWORD dst_unused:UNUSED_PAD src0_sel:WORD_1
	v_cvt_f32_f16_e32 v36, v9
	v_cvt_f32_f16_sdwa v37, v9 dst_sel:DWORD dst_unused:UNUSED_PAD src0_sel:WORD_1
	v_cvt_f32_f16_e32 v38, v10
	v_cvt_f32_f16_sdwa v39, v10 dst_sel:DWORD dst_unused:UNUSED_PAD src0_sel:WORD_1
	v_cvt_f32_f16_e32 v40, v11
	v_cvt_f32_f16_sdwa v41, v11 dst_sel:DWORD dst_unused:UNUSED_PAD src0_sel:WORD_1
	v_cvt_f32_f16_e32 v42, v12
	v_cvt_f32_f16_sdwa v43, v12 dst_sel:DWORD dst_unused:UNUSED_PAD src0_sel:WORD_1
	v_cvt_f32_f16_e32 v44, v13
	v_cvt_f32_f16_sdwa v45, v13 dst_sel:DWORD dst_unused:UNUSED_PAD src0_sel:WORD_1
	v_cvt_f32_f16_e32 v46, v14
	v_cvt_f32_f16_sdwa v47, v14 dst_sel:DWORD dst_unused:UNUSED_PAD src0_sel:WORD_1
	v_cvt_f32_f16_e32 v48, v15
	v_cvt_f32_f16_sdwa v49, v15 dst_sel:DWORD dst_unused:UNUSED_PAD src0_sel:WORD_1
	v_cvt_f32_f16_e32 v50, v16
	v_cvt_f32_f16_sdwa v51, v16 dst_sel:DWORD dst_unused:UNUSED_PAD src0_sel:WORD_1
	v_cvt_f32_f16_e32 v52, v17
	v_cvt_f32_f16_sdwa v53, v17 dst_sel:DWORD dst_unused:UNUSED_PAD src0_sel:WORD_1
	s_waitcnt lgkmcnt(8)
	v_pk_mul_f32 v[86:87], v[22:23], v[54:55]
	v_pk_mul_f32 v[88:89], v[24:25], v[56:57]
	v_pk_fma_f32 v[86:87], v[26:27], v[58:59], v[86:87]
	v_pk_fma_f32 v[88:89], v[28:29], v[60:61], v[88:89]
	v_pk_fma_f32 v[86:87], v[30:31], v[62:63], v[86:87]
	v_pk_fma_f32 v[88:89], v[32:33], v[64:65], v[88:89]
	v_pk_fma_f32 v[86:87], v[34:35], v[66:67], v[86:87]
	v_pk_fma_f32 v[88:89], v[36:37], v[68:69], v[88:89]
	v_pk_fma_f32 v[86:87], v[38:39], v[70:71], v[86:87]
	v_pk_fma_f32 v[88:89], v[40:41], v[72:73], v[88:89]
	v_pk_fma_f32 v[86:87], v[42:43], v[74:75], v[86:87]
	v_pk_fma_f32 v[88:89], v[44:45], v[76:77], v[88:89]
	v_pk_fma_f32 v[86:87], v[46:47], v[78:79], v[86:87]
	v_pk_fma_f32 v[88:89], v[48:49], v[80:81], v[88:89]
	v_pk_fma_f32 v[86:87], v[50:51], v[82:83], v[86:87]
	v_pk_fma_f32 v[88:89], v[52:53], v[84:85], v[88:89]
	ds_read_b128 v[54:57], v100 offset:512
	ds_read_b128 v[58:61], v100 offset:528
	ds_read_b128 v[62:65], v100 offset:576
	ds_read_b128 v[66:69], v100 offset:592
	ds_read_b128 v[70:73], v100 offset:640
	ds_read_b128 v[74:77], v100 offset:656
	ds_read_b128 v[78:81], v100 offset:704
	ds_read_b128 v[82:85], v100 offset:720
	v_pk_add_f32 v[86:87], v[86:87], v[88:89]
	s_nop 0
	v_add_f32_e32 v138, v86, v87
	s_waitcnt lgkmcnt(8)
; __device__ __forceinline__ unsigned moba_select(int b, int h, int qb, const f16_t* Q, const float* __restrict__ kms) {
;     ...
;     for (int j = 0; j < 7; ++j) {
;         float s = 0.f;
;         if (j < qb) {
;             const float* km = kms + (size_t)(b * NBLK + j) * AW + h * HD + hi * 8;
; #pragma unroll
;             for (int d0 = 0; d0 < 4; ++d0) {
;                 const f32x4 k0 = *(const f32x4*)(km + d0 * 16), k1 = *(const f32x4*)(km + d0 * 16 + 4);
;                 s += (float)qr[d0][0] * k0[0] + (float)qr[d0][1] * k0[1] + (float)qr[d0][2] * k0[2] + (float)qr[d0][3] * k0[3];
;                 s += (float)qr[d0][4] * k1[0] + (float)qr[d0][5] * k1[1] + (float)qr[d0][6] * k1[2] + (float)qr[d0][7] * k1[3];
;             }
;             s += __shfl_xor(s, 32);
	v_pk_mul_f32 v[90:91], v[22:23], v[106:107]
	v_pk_mul_f32 v[92:93], v[24:25], v[108:109]
	v_pk_fma_f32 v[90:91], v[26:27], v[110:111], v[90:91]
	v_pk_fma_f32 v[92:93], v[28:29], v[112:113], v[92:93]
	v_pk_fma_f32 v[90:91], v[30:31], v[114:115], v[90:91]
	v_pk_fma_f32 v[92:93], v[32:33], v[116:117], v[92:93]
	v_pk_fma_f32 v[90:91], v[34:35], v[118:119], v[90:91]
	v_pk_fma_f32 v[92:93], v[36:37], v[120:121], v[92:93]
	v_pk_fma_f32 v[90:91], v[38:39], v[122:123], v[90:91]
	v_pk_fma_f32 v[92:93], v[40:41], v[124:125], v[92:93]
	v_pk_fma_f32 v[90:91], v[42:43], v[126:127], v[90:91]
	v_pk_fma_f32 v[92:93], v[44:45], v[128:129], v[92:93]
	v_pk_fma_f32 v[90:91], v[46:47], v[130:131], v[90:91]
	v_pk_fma_f32 v[92:93], v[48:49], v[132:133], v[92:93]
	v_pk_fma_f32 v[90:91], v[50:51], v[134:135], v[90:91]
	v_pk_fma_f32 v[92:93], v[52:53], v[136:137], v[92:93]
	ds_read_b128 v[106:109], v100 offset:768
	ds_read_b128 v[110:113], v100 offset:784
	ds_read_b128 v[114:117], v100 offset:832
	ds_read_b128 v[118:121], v100 offset:848
	ds_read_b128 v[122:125], v100 offset:896
	ds_read_b128 v[126:129], v100 offset:912
	ds_read_b128 v[130:133], v100 offset:960
	ds_read_b128 v[134:137], v100 offset:976
	v_pk_add_f32 v[90:91], v[90:91], v[92:93]
	s_nop 0
	v_add_f32_e32 v139, v90, v91
	s_waitcnt lgkmcnt(8)
	v_pk_mul_f32 v[86:87], v[22:23], v[54:55]
	v_pk_mul_f32 v[88:89], v[24:25], v[56:57]
	v_pk_fma_f32 v[86:87], v[26:27], v[58:59], v[86:87]
	v_pk_fma_f32 v[88:89], v[28:29], v[60:61], v[88:89]
	v_pk_fma_f32 v[86:87], v[30:31], v[62:63], v[86:87]
	v_pk_fma_f32 v[88:89], v[32:33], v[64:65], v[88:89]
	v_pk_fma_f32 v[86:87], v[34:35], v[66:67], v[86:87]
	v_pk_fma_f32 v[88:89], v[36:37], v[68:69], v[88:89]
	v_pk_fma_f32 v[86:87], v[38:39], v[70:71], v[86:87]
	v_pk_fma_f32 v[88:89], v[40:41], v[72:73], v[88:89]
	v_pk_fma_f32 v[86:87], v[42:43], v[74:75], v[86:87]
	v_pk_fma_f32 v[88:89], v[44:45], v[76:77], v[88:89]
	v_pk_fma_f32 v[86:87], v[46:47], v[78:79], v[86:87]
	v_pk_fma_f32 v[88:89], v[48:49], v[80:81], v[88:89]
	v_pk_fma_f32 v[86:87], v[50:51], v[82:83], v[86:87]
	v_pk_fma_f32 v[88:89], v[52:53], v[84:85], v[88:89]
	ds_read_b128 v[54:57], v100 offset:1024
	ds_read_b128 v[58:61], v100 offset:1040
	ds_read_b128 v[62:65], v100 offset:1088
	ds_read_b128 v[66:69], v100 offset:1104
	ds_read_b128 v[70:73], v100 offset:1152
	ds_read_b128 v[74:77], v100 offset:1168
	ds_read_b128 v[78:81], v100 offset:1216
	ds_read_b128 v[82:85], v100 offset:1232
	v_pk_add_f32 v[86:87], v[86:87], v[88:89]
	s_nop 0
	v_add_f32_e32 v140, v86, v87
	s_waitcnt lgkmcnt(8)
	v_pk_mul_f32 v[90:91], v[22:23], v[106:107]
	v_pk_mul_f32 v[92:93], v[24:25], v[108:109]
	v_pk_fma_f32 v[90:91], v[26:27], v[110:111], v[90:91]
	v_pk_fma_f32 v[92:93], v[28:29], v[112:113], v[92:93]
	v_pk_fma_f32 v[90:91], v[30:31], v[114:115], v[90:91]
	v_pk_fma_f32 v[92:93], v[32:33], v[116:117], v[92:93]
	v_pk_fma_f32 v[90:91], v[34:35], v[118:119], v[90:91]
	v_pk_fma_f32 v[92:93], v[36:37], v[120:121], v[92:93]
	v_pk_fma_f32 v[90:91], v[38:39], v[122:123], v[90:91]
	v_pk_fma_f32 v[92:93], v[40:41], v[124:125], v[92:93]
	v_pk_fma_f32 v[90:91], v[42:43], v[126:127], v[90:91]
	v_pk_fma_f32 v[92:93], v[44:45], v[128:129], v[92:93]
	v_pk_fma_f32 v[90:91], v[46:47], v[130:131], v[90:91]
	v_pk_fma_f32 v[92:93], v[48:49], v[132:133], v[92:93]
	v_pk_fma_f32 v[90:91], v[50:51], v[134:135], v[90:91]
	v_pk_fma_f32 v[92:93], v[52:53], v[136:137], v[92:93]
	ds_read_b128 v[106:109], v100 offset:1280
	ds_read_b128 v[110:113], v100 offset:1296
	ds_read_b128 v[114:117], v100 offset:1344
	ds_read_b128 v[118:121], v100 offset:1360
	ds_read_b128 v[122:125], v100 offset:1408
	ds_read_b128 v[126:129], v100 offset:1424
	ds_read_b128 v[130:133], v100 offset:1472
	ds_read_b128 v[134:137], v100 offset:1488
	v_pk_add_f32 v[90:91], v[90:91], v[92:93]
	s_nop 0
	v_add_f32_e32 v141, v90, v91
	s_waitcnt lgkmcnt(8)
	v_pk_mul_f32 v[86:87], v[22:23], v[54:55]
	v_pk_mul_f32 v[88:89], v[24:25], v[56:57]
	v_pk_fma_f32 v[86:87], v[26:27], v[58:59], v[86:87]
	v_pk_fma_f32 v[88:89], v[28:29], v[60:61], v[88:89]
	v_pk_fma_f32 v[86:87], v[30:31], v[62:63], v[86:87]
	v_pk_fma_f32 v[88:89], v[32:33], v[64:65], v[88:89]
	v_pk_fma_f32 v[86:87], v[34:35], v[66:67], v[86:87]
	v_pk_fma_f32 v[88:89], v[36:37], v[68:69], v[88:89]
	v_pk_fma_f32 v[86:87], v[38:39], v[70:71], v[86:87]
	v_pk_fma_f32 v[88:89], v[40:41], v[72:73], v[88:89]
	v_pk_fma_f32 v[86:87], v[42:43], v[74:75], v[86:87]
	v_pk_fma_f32 v[88:89], v[44:45], v[76:77], v[88:89]
	v_pk_fma_f32 v[86:87], v[46:47], v[78:79], v[86:87]
	v_pk_fma_f32 v[88:89], v[48:49], v[80:81], v[88:89]
	v_pk_fma_f32 v[86:87], v[50:51], v[82:83], v[86:87]
	v_pk_fma_f32 v[88:89], v[52:53], v[84:85], v[88:89]
	ds_read_b128 v[54:57], v100 offset:1536
	ds_read_b128 v[58:61], v100 offset:1552
	ds_read_b128 v[62:65], v100 offset:1600
	ds_read_b128 v[66:69], v100 offset:1616
	ds_read_b128 v[70:73], v100 offset:1664
	ds_read_b128 v[74:77], v100 offset:1680
	ds_read_b128 v[78:81], v100 offset:1728
	ds_read_b128 v[82:85], v100 offset:1744
	v_pk_add_f32 v[86:87], v[86:87], v[88:89]
	s_nop 0
	v_add_f32_e32 v142, v86, v87
	s_waitcnt lgkmcnt(8)
	v_pk_mul_f32 v[90:91], v[22:23], v[106:107]
	v_pk_mul_f32 v[92:93], v[24:25], v[108:109]
	v_pk_fma_f32 v[90:91], v[26:27], v[110:111], v[90:91]
	v_pk_fma_f32 v[92:93], v[28:29], v[112:113], v[92:93]
	v_pk_fma_f32 v[90:91], v[30:31], v[114:115], v[90:91]
	v_pk_fma_f32 v[92:93], v[32:33], v[116:117], v[92:93]
	v_pk_fma_f32 v[90:91], v[34:35], v[118:119], v[90:91]
	v_pk_fma_f32 v[92:93], v[36:37], v[120:121], v[92:93]
	v_pk_fma_f32 v[90:91], v[38:39], v[122:123], v[90:91]
	v_pk_fma_f32 v[92:93], v[40:41], v[124:125], v[92:93]
	v_pk_fma_f32 v[90:91], v[42:43], v[126:127], v[90:91]
	v_pk_fma_f32 v[92:93], v[44:45], v[128:129], v[92:93]
	v_pk_fma_f32 v[90:91], v[46:47], v[130:131], v[90:91]
	v_pk_fma_f32 v[92:93], v[48:49], v[132:133], v[92:93]
	v_pk_fma_f32 v[90:91], v[50:51], v[134:135], v[90:91]
	v_pk_fma_f32 v[92:93], v[52:53], v[136:137], v[92:93]
	s_nop 0
	v_pk_add_f32 v[90:91], v[90:91], v[92:93]
	s_nop 0
	v_add_f32_e32 v143, v90, v91
	s_waitcnt lgkmcnt(0)
; __device__ __forceinline__ unsigned moba_select(int b, int h, int qb, const f16_t* Q, const float* __restrict__ kms) {
;     ...
;     for (int j = 0; j < 7; ++j) {
;         float s = 0.f;
;         if (j < qb) {
;             const float* km = kms + (size_t)(b * NBLK + j) * AW + h * HD + hi * 8;
; #pragma unroll
;             for (int d0 = 0; d0 < 4; ++d0) {
;                 const f32x4 k0 = *(const f32x4*)(km + d0 * 16), k1 = *(const f32x4*)(km + d0 * 16 + 4);
;                 s += (float)qr[d0][0] * k0[0] + (float)qr[d0][1] * k0[1] + (float)qr[d0][2] * k0[2] + (float)qr[d0][3] * k0[3];
;                 s += (float)qr[d0][4] * k1[0] + (float)qr[d0][5] * k1[1] + (float)qr[d0][6] * k1[2] + (float)qr[d0][7] * k1[3];
;             }
;             s += __shfl_xor(s, 32);
;         } else s = -INFINITY;
;         gsc[j] = s;
;     }
;     unsigned sm = 0u;
; #pragma unroll
;     for (int j = 0; j < 7; ++j) {
;         int cnt = 0;
; #pragma unroll
;         for (int i = 0; i < 7; ++i) { if (i == j) continue; const bool ahead = (gsc[i] > gsc[j]) || (gsc[i] == gsc[j] && i < j); cnt += ahead ? 1 : 0; }
;         if (j < qb && cnt < 3) sm |= (1u << j);
;     }
;     return sm;
	v_pk_mul_f32 v[86:87], v[22:23], v[54:55]
	v_pk_mul_f32 v[88:89], v[24:25], v[56:57]
	v_pk_fma_f32 v[86:87], v[26:27], v[58:59], v[86:87]
	v_pk_fma_f32 v[88:89], v[28:29], v[60:61], v[88:89]
	v_pk_fma_f32 v[86:87], v[30:31], v[62:63], v[86:87]
	v_pk_fma_f32 v[88:89], v[32:33], v[64:65], v[88:89]
	v_pk_fma_f32 v[86:87], v[34:35], v[66:67], v[86:87]
	v_pk_fma_f32 v[88:89], v[36:37], v[68:69], v[88:89]
	v_pk_fma_f32 v[86:87], v[38:39], v[70:71], v[86:87]
	v_pk_fma_f32 v[88:89], v[40:41], v[72:73], v[88:89]
	v_pk_fma_f32 v[86:87], v[42:43], v[74:75], v[86:87]
	v_pk_fma_f32 v[88:89], v[44:45], v[76:77], v[88:89]
	v_pk_fma_f32 v[86:87], v[46:47], v[78:79], v[86:87]
	v_pk_fma_f32 v[88:89], v[48:49], v[80:81], v[88:89]
	v_pk_fma_f32 v[86:87], v[50:51], v[82:83], v[86:87]
	v_pk_fma_f32 v[88:89], v[52:53], v[84:85], v[88:89]
	s_nop 0
	v_pk_add_f32 v[86:87], v[86:87], v[88:89]
	s_nop 0
	v_add_f32_e32 v144, v86, v87
	v_mov_b32_e32 v54, v138
	v_mov_b32_e32 v55, v139
	v_mov_b32_e32 v56, v140
	v_mov_b32_e32 v57, v141
	v_mov_b32_e32 v58, v142
	v_mov_b32_e32 v59, v143
	v_mov_b32_e32 v60, v144
	s_nop 1
	v_permlane32_swap_b32_e32 v138, v54
	v_permlane32_swap_b32_e32 v139, v55
	v_permlane32_swap_b32_e32 v140, v56
	v_permlane32_swap_b32_e32 v141, v57
	v_permlane32_swap_b32_e32 v142, v58
	v_permlane32_swap_b32_e32 v143, v59
	v_permlane32_swap_b32_e32 v144, v60
	v_add_f32_e32 v138, v138, v54
	v_add_f32_e32 v139, v139, v55
	v_add_f32_e32 v140, v140, v56
	v_add_f32_e32 v141, v141, v57
	v_add_f32_e32 v142, v142, v58
	v_add_f32_e32 v143, v143, v59
	v_add_f32_e32 v144, v144, v60
	v_mov_b32_e32 v146, 0xff800000
	s_cmp_gt_u32 s70, 4
	s_cselect_b64 s[30:31], -1, 0
	v_cndmask_b32_e64 v142, v146, v142, s[30:31]
	s_cmp_gt_u32 s70, 5
	s_cselect_b64 s[30:31], -1, 0
	v_cndmask_b32_e64 v143, v146, v143, s[30:31]
	s_cmp_gt_u32 s70, 6
	s_cselect_b64 s[30:31], -1, 0
	v_cndmask_b32_e64 v144, v146, v144, s[30:31]
	v_mov_b32_e32 v151, 6
	v_mov_b32_e32 v152, 5
	v_mov_b32_e32 v153, 4
	v_mov_b32_e32 v154, 3
	v_mov_b32_e32 v155, 2
	v_mov_b32_e32 v156, 1
	v_mov_b32_e32 v157, 0
	v_cmp_ge_f32_e64 s[0:1], v138, v139
	v_cmp_ge_f32_e64 s[30:31], v138, v140
	v_cmp_ge_f32_e64 s[36:37], v138, v141
	v_addc_co_u32_e64 v152, s[100:101], 0, v152, s[0:1]
	v_subb_co_u32_e64 v151, s[100:101], v151, 0, s[0:1]
	v_cmp_ge_f32_e64 s[98:99], v138, v142
	v_addc_co_u32_e64 v153, s[100:101], 0, v153, s[30:31]
	v_subb_co_u32_e64 v151, s[100:101], v151, 0, s[30:31]
	v_cmp_ge_f32_e64 s[0:1], v138, v143
	v_addc_co_u32_e64 v154, s[100:101], 0, v154, s[36:37]
	v_subb_co_u32_e64 v151, s[100:101], v151, 0, s[36:37]
	v_cmp_ge_f32_e64 s[30:31], v138, v144
	v_addc_co_u32_e64 v155, s[100:101], 0, v155, s[98:99]
	v_subb_co_u32_e64 v151, s[100:101], v151, 0, s[98:99]
	v_cmp_ge_f32_e64 s[36:37], v139, v140
	v_addc_co_u32_e64 v156, s[100:101], 0, v156, s[0:1]
	v_subb_co_u32_e64 v151, s[100:101], v151, 0, s[0:1]
	v_cmp_ge_f32_e64 s[98:99], v139, v141
	v_addc_co_u32_e64 v157, s[100:101], 0, v157, s[30:31]
	v_subb_co_u32_e64 v151, s[100:101], v151, 0, s[30:31]
	v_cmp_ge_f32_e64 s[0:1], v139, v142
	v_addc_co_u32_e64 v153, s[100:101], 0, v153, s[36:37]
	v_subb_co_u32_e64 v152, s[100:101], v152, 0, s[36:37]
	v_cmp_ge_f32_e64 s[30:31], v139, v143
	v_addc_co_u32_e64 v154, s[100:101], 0, v154, s[98:99]
	v_subb_co_u32_e64 v152, s[100:101], v152, 0, s[98:99]
	v_cmp_ge_f32_e64 s[36:37], v139, v144
	v_addc_co_u32_e64 v155, s[100:101], 0, v155, s[0:1]
	v_subb_co_u32_e64 v152, s[100:101], v152, 0, s[0:1]
	v_cmp_ge_f32_e64 s[98:99], v140, v141
	v_addc_co_u32_e64 v156, s[100:101], 0, v156, s[30:31]
	v_subb_co_u32_e64 v152, s[100:101], v152, 0, s[30:31]
	v_cmp_ge_f32_e64 s[0:1], v140, v142
	v_addc_co_u32_e64 v157, s[100:101], 0, v157, s[36:37]
	v_subb_co_u32_e64 v152, s[100:101], v152, 0, s[36:37]
	v_cmp_ge_f32_e64 s[30:31], v140, v143
	v_addc_co_u32_e64 v154, s[100:101], 0, v154, s[98:99]
	v_subb_co_u32_e64 v153, s[100:101], v153, 0, s[98:99]
	v_cmp_ge_f32_e64 s[36:37], v140, v144
	v_addc_co_u32_e64 v155, s[100:101], 0, v155, s[0:1]
	v_subb_co_u32_e64 v153, s[100:101], v153, 0, s[0:1]
	v_cmp_ge_f32_e64 s[98:99], v141, v142
	v_addc_co_u32_e64 v156, s[100:101], 0, v156, s[30:31]
	v_subb_co_u32_e64 v153, s[100:101], v153, 0, s[30:31]
	v_cmp_ge_f32_e64 s[0:1], v141, v143
	v_addc_co_u32_e64 v157, s[100:101], 0, v157, s[36:37]
	v_subb_co_u32_e64 v153, s[100:101], v153, 0, s[36:37]
	v_cmp_ge_f32_e64 s[30:31], v141, v144
	v_addc_co_u32_e64 v155, s[100:101], 0, v155, s[98:99]
	v_subb_co_u32_e64 v154, s[100:101], v154, 0, s[98:99]
	v_cmp_ge_f32_e64 s[36:37], v142, v143
	v_addc_co_u32_e64 v156, s[100:101], 0, v156, s[0:1]
	v_subb_co_u32_e64 v154, s[100:101], v154, 0, s[0:1]
	v_cmp_ge_f32_e64 s[98:99], v142, v144
	v_addc_co_u32_e64 v157, s[100:101], 0, v157, s[30:31]
	v_subb_co_u32_e64 v154, s[100:101], v154, 0, s[30:31]
	v_cmp_ge_f32_e64 s[0:1], v143, v144
	v_addc_co_u32_e64 v156, s[100:101], 0, v156, s[36:37]
	v_subb_co_u32_e64 v155, s[100:101], v155, 0, s[36:37]
	s_nop 0
	v_addc_co_u32_e64 v157, s[100:101], 0, v157, s[98:99]
	v_subb_co_u32_e64 v155, s[100:101], v155, 0, s[98:99]
	s_nop 0
	v_addc_co_u32_e64 v157, s[100:101], 0, v157, s[0:1]
	v_subb_co_u32_e64 v156, s[100:101], v156, 0, s[0:1]
	s_nop 1
	v_cmp_gt_u32_e64 s[0:1], 3, v151
	v_cmp_gt_u32_e64 s[30:31], 3, v152
	v_cmp_gt_u32_e64 s[36:37], 3, v153
	v_cndmask_b32_e64 v147, 0, 1, s[0:1]
	v_cmp_gt_u32_e64 s[98:99], 3, v154
	v_cndmask_b32_e64 v148, 0, 2, s[30:31]
	v_cmp_gt_u32_e64 s[0:1], 3, v155
	v_cndmask_b32_e64 v149, 0, 4, s[36:37]
	v_cmp_gt_u32_e64 s[30:31], 3, v156
	v_cndmask_b32_e64 v158, 0, 8, s[98:99]
	v_cmp_gt_u32_e64 s[36:37], 3, v157
	v_cndmask_b32_e64 v159, 0, 16, s[0:1]
	s_nop 0
	v_cndmask_b32_e64 v160, 0, 32, s[30:31]
	v_cndmask_b32_e64 v161, 0, 64, s[36:37]
	s_lshl_b32 s9, 1, s70
	s_add_i32 s9, s9, -1
	v_or3_b32 v210, v147, v148, v149
	v_or3_b32 v210, v210, v158, v159
	v_or3_b32 v210, v210, v160, v161
	v_and_b32_e32 v210, s9, v210
